# G2 layer-0 K-loop last trip: plain loads touch the f32 residual tile (input x) so the epilogue's reads hit L2
# baseline (speedup 1.0000x reference)
.LBB0_812:
	s_add_u32 s14, s42, 0xfffc0080
	s_addc_u32 s15, s43, -1
	s_add_i32 s24, 0, 0x10000
	s_cmp_eq_u32 s91, 12
	s_cselect_b32 s55, s16, s15
	s_cselect_b32 s54, s17, s14
	s_cselect_b32 s15, s39, s89
	s_cselect_b32 s14, s47, s87
	s_cmp_lg_u32 s91, 12
	s_cbranch_scc1 .Ltouch_g2_skip
	s_cmp_eq_u64 s[6:7], 0
	s_cbranch_scc1 .Ltouch_g2_skip
	v_lshrrev_b32_e32 v249, 3, v194
	v_lshlrev_b32_e32 v249, 12, v249
	v_and_b32_e32 v248, 7, v194
	v_lshl_add_u32 v249, v248, 7, v249
	s_lshl_b32 s100, s77, 20
	s_lshl_b32 s101, s76, 10
	s_add_u32 s100, s100, s101
	s_add_u32 s100, s6, s100
	s_addc_u32 s101, s7, 0
	s_nop 0
	global_load_dword v248, v249, s[100:101]
	s_add_u32 s100, s100, 0x40000
	s_addc_u32 s101, s101, 0
	s_nop 0
	global_load_dword v248, v249, s[100:101]
	s_add_u32 s100, s100, 0x40000
	s_addc_u32 s101, s101, 0
	s_nop 0
	global_load_dword v248, v249, s[100:101]
	s_add_u32 s100, s100, 0x40000
	s_addc_u32 s101, s101, 0
	s_nop 0
	global_load_dword v248, v249, s[100:101]
.Ltouch_g2_skip:
	s_add_i32 s25, 0, 0x14000
	v_add_u32_e32 v152, s24, v175
	v_add_u32_e32 v172, s25, v175
	ds_read_b128 v[132:135], v152
	ds_read_b128 v[136:139], v152 offset:1024
	ds_read_b128 v[148:151], v152 offset:2048
	ds_read_b128 v[152:155], v152 offset:3072
	ds_read_b128 v[178:181], v172
	ds_read_b128 v[182:185], v172 offset:1024
	ds_read_b128 v[186:189], v172 offset:2048
	ds_read_b128 v[190:193], v172 offset:3072
	v_lshl_add_u64 v[172:173], s[42:43], 0, v[146:147]
	s_add_i32 m0, s23, 0xc000
	ds_read_b128 v[200:203], v177
	ds_read_b128 v[204:207], v177 offset:1024
	ds_read_b128 v[208:211], v177 offset:2048
	ds_read_b128 v[212:215], v177 offset:3072
	ds_read_b128 v[216:219], v177 offset:4096
	ds_read_b128 v[220:223], v177 offset:5120
	ds_read_b128 v[224:227], v177 offset:6144
	ds_read_b128 v[228:231], v177 offset:7168
	global_load_lds_dwordx4 v[172:173], off
	v_lshl_add_u64 v[172:173], s[42:43], 0, v[144:145]
	s_add_i32 m0, s23, 0xe000
	s_nop 0
	global_load_lds_dwordx4 v[172:173], off
	s_waitcnt vmcnt(8)
	s_waitcnt lgkmcnt(0)
	s_barrier
	s_setprio 1
	s_waitcnt lgkmcnt(0)
	v_mfma_f32_16x16x32_bf16 v[128:131], v[132:135], v[200:203], v[128:131]
	v_mfma_f32_16x16x32_bf16 v[124:127], v[148:151], v[200:203], v[124:127]
	v_mfma_f32_16x16x32_bf16 v[112:115], v[132:135], v[208:211], v[112:115]
	v_mfma_f32_16x16x32_bf16 v[108:111], v[148:151], v[208:211], v[108:111]
	v_mfma_f32_16x16x32_bf16 v[96:99], v[132:135], v[216:219], v[96:99]
	v_mfma_f32_16x16x32_bf16 v[92:95], v[148:151], v[216:219], v[92:95]
	v_mfma_f32_16x16x32_bf16 v[80:83], v[132:135], v[224:227], v[80:83]
	v_mfma_f32_16x16x32_bf16 v[76:79], v[148:151], v[224:227], v[76:79]
	v_mfma_f32_16x16x32_bf16 v[128:131], v[136:139], v[204:207], v[128:131]
	v_mfma_f32_16x16x32_bf16 v[124:127], v[152:155], v[204:207], v[124:127]
	v_mfma_f32_16x16x32_bf16 v[112:115], v[136:139], v[212:215], v[112:115]
	v_mfma_f32_16x16x32_bf16 v[108:111], v[152:155], v[212:215], v[108:111]
	v_mfma_f32_16x16x32_bf16 v[96:99], v[136:139], v[220:223], v[96:99]
	v_mfma_f32_16x16x32_bf16 v[92:95], v[152:155], v[220:223], v[92:95]
	v_mfma_f32_16x16x32_bf16 v[80:83], v[136:139], v[228:231], v[80:83]
	v_mfma_f32_16x16x32_bf16 v[76:79], v[152:155], v[228:231], v[76:79]
	s_setprio 0
	s_setprio 1
	v_mfma_f32_16x16x32_bf16 v[120:123], v[178:181], v[200:203], v[120:123]
	v_mfma_f32_16x16x32_bf16 v[116:119], v[186:189], v[200:203], v[116:119]
	v_mfma_f32_16x16x32_bf16 v[104:107], v[178:181], v[208:211], v[104:107]
	v_mfma_f32_16x16x32_bf16 v[100:103], v[186:189], v[208:211], v[100:103]
	v_mfma_f32_16x16x32_bf16 v[88:91], v[178:181], v[216:219], v[88:91]
	v_mfma_f32_16x16x32_bf16 v[84:87], v[186:189], v[216:219], v[84:87]
	v_mfma_f32_16x16x32_bf16 v[72:75], v[178:181], v[224:227], v[72:75]
	v_mfma_f32_16x16x32_bf16 v[68:71], v[186:189], v[224:227], v[68:71]
	v_mfma_f32_16x16x32_bf16 v[120:123], v[182:185], v[204:207], v[120:123]
	v_mfma_f32_16x16x32_bf16 v[116:119], v[190:193], v[204:207], v[116:119]
	v_mfma_f32_16x16x32_bf16 v[104:107], v[182:185], v[212:215], v[104:107]
	v_mfma_f32_16x16x32_bf16 v[100:103], v[190:193], v[212:215], v[100:103]
	v_mfma_f32_16x16x32_bf16 v[88:91], v[182:185], v[220:223], v[88:91]
	v_mfma_f32_16x16x32_bf16 v[84:87], v[190:193], v[220:223], v[84:87]
	v_mfma_f32_16x16x32_bf16 v[72:75], v[182:185], v[228:231], v[72:75]
	v_mfma_f32_16x16x32_bf16 v[68:71], v[190:193], v[228:231], v[68:71]
	s_setprio 0
	s_barrier
	s_add_i32 s24, s24, s22
	v_lshl_add_u64 v[172:173], s[14:15], 0, v[2:3]
	s_mov_b32 m0, s24
	ds_read_b128 v[200:203], v177 offset:16384
	ds_read_b128 v[204:207], v177 offset:17408
	ds_read_b128 v[208:211], v177 offset:18432
	ds_read_b128 v[212:215], v177 offset:19456
	ds_read_b128 v[216:219], v177 offset:20480
	ds_read_b128 v[220:223], v177 offset:21504
	ds_read_b128 v[224:227], v177 offset:22528
	ds_read_b128 v[228:231], v177 offset:23552
	global_load_lds_dwordx4 v[172:173], off
	s_add_i32 m0, s24, 0x2000
	s_add_u32 s96, s14, 0x40000
	v_lshl_add_u64 v[232:233], s[14:15], 0, v[0:1]
	s_addc_u32 s97, s15, 0
	s_add_i32 s24, s25, s22
	global_load_lds_dwordx4 v[232:233], off
	v_lshl_add_u64 v[234:235], s[96:97], 0, v[2:3]
	s_mov_b32 m0, s24
	v_lshl_add_u64 v[236:237], s[54:55], 0, v[140:141]
	global_load_lds_dwordx4 v[234:235], off
	v_lshl_add_u64 v[234:235], s[96:97], 0, v[0:1]
	s_add_i32 m0, s24, 0x2000
	s_nop 0
	global_load_lds_dwordx4 v[234:235], off
	v_lshl_add_u64 v[234:235], s[54:55], 0, v[142:143]
	s_mov_b32 m0, s23
	s_nop 0
	global_load_lds_dwordx4 v[234:235], off
	s_mov_b32 m0, s45
	s_nop 0
	global_load_lds_dwordx4 v[236:237], off
	s_waitcnt vmcnt(8)
	s_waitcnt lgkmcnt(0)
	s_barrier
	s_setprio 1
	s_waitcnt lgkmcnt(0)
	v_mfma_f32_16x16x32_bf16 v[64:67], v[132:135], v[200:203], v[64:67]
	v_mfma_f32_16x16x32_bf16 v[60:63], v[148:151], v[200:203], v[60:63]
	v_mfma_f32_16x16x32_bf16 v[48:51], v[132:135], v[208:211], v[48:51]
	v_mfma_f32_16x16x32_bf16 v[44:47], v[148:151], v[208:211], v[44:47]
	v_mfma_f32_16x16x32_bf16 v[32:35], v[132:135], v[216:219], v[32:35]
	v_mfma_f32_16x16x32_bf16 v[28:31], v[148:151], v[216:219], v[28:31]
	v_mfma_f32_16x16x32_bf16 v[16:19], v[132:135], v[224:227], v[16:19]
	v_mfma_f32_16x16x32_bf16 v[12:15], v[148:151], v[224:227], v[12:15]
	v_mfma_f32_16x16x32_bf16 v[64:67], v[136:139], v[204:207], v[64:67]
	v_mfma_f32_16x16x32_bf16 v[60:63], v[152:155], v[204:207], v[60:63]
	v_mfma_f32_16x16x32_bf16 v[48:51], v[136:139], v[212:215], v[48:51]
	v_mfma_f32_16x16x32_bf16 v[44:47], v[152:155], v[212:215], v[44:47]
	v_mfma_f32_16x16x32_bf16 v[32:35], v[136:139], v[220:223], v[32:35]
	v_mfma_f32_16x16x32_bf16 v[28:31], v[152:155], v[220:223], v[28:31]
	v_mfma_f32_16x16x32_bf16 v[16:19], v[136:139], v[228:231], v[16:19]
	v_mfma_f32_16x16x32_bf16 v[12:15], v[152:155], v[228:231], v[12:15]
	s_setprio 0
	s_setprio 1
	v_mfma_f32_16x16x32_bf16 v[56:59], v[178:181], v[200:203], v[56:59]
	v_mfma_f32_16x16x32_bf16 v[52:55], v[186:189], v[200:203], v[52:55]
	v_mfma_f32_16x16x32_bf16 v[40:43], v[178:181], v[208:211], v[40:43]
	v_mfma_f32_16x16x32_bf16 v[36:39], v[186:189], v[208:211], v[36:39]
	v_mfma_f32_16x16x32_bf16 v[24:27], v[178:181], v[216:219], v[24:27]
	v_mfma_f32_16x16x32_bf16 v[20:23], v[186:189], v[216:219], v[20:23]
	v_mfma_f32_16x16x32_bf16 v[8:11], v[178:181], v[224:227], v[8:11]
	v_mfma_f32_16x16x32_bf16 v[4:7], v[186:189], v[224:227], v[4:7]
	v_mfma_f32_16x16x32_bf16 v[56:59], v[182:185], v[204:207], v[56:59]
	v_mfma_f32_16x16x32_bf16 v[52:55], v[190:193], v[204:207], v[52:55]
	v_mfma_f32_16x16x32_bf16 v[40:43], v[182:185], v[212:215], v[40:43]
	v_mfma_f32_16x16x32_bf16 v[36:39], v[190:193], v[212:215], v[36:39]
	v_mfma_f32_16x16x32_bf16 v[24:27], v[182:185], v[220:223], v[24:27]
	v_mfma_f32_16x16x32_bf16 v[20:23], v[190:193], v[220:223], v[20:23]
	v_mfma_f32_16x16x32_bf16 v[8:11], v[182:185], v[228:231], v[8:11]
	v_mfma_f32_16x16x32_bf16 v[4:7], v[190:193], v[228:231], v[4:7]
	s_setprio 0
	s_barrier
	s_add_i32 s24, 0, 0x18000
	s_add_i32 s25, 0, 0x1c000
	v_add_u32_e32 v152, s24, v175
	v_add_u32_e32 v190, s25, v175
	ds_read_b128 v[132:135], v152
	ds_read_b128 v[136:139], v152 offset:1024
	ds_read_b128 v[148:151], v152 offset:2048
	ds_read_b128 v[152:155], v152 offset:3072
	ds_read_b128 v[178:181], v190
	ds_read_b128 v[182:185], v190 offset:1024
	ds_read_b128 v[186:189], v190 offset:2048
	ds_read_b128 v[190:193], v190 offset:3072
	s_add_u32 s54, s54, 0x40000
	s_addc_u32 s55, s55, 0
	s_mov_b32 m0, s60
	v_lshl_add_u64 v[238:239], s[54:55], 0, v[142:143]
	ds_read_b128 v[200:203], v177 offset:32768
	ds_read_b128 v[204:207], v177 offset:33792
	ds_read_b128 v[208:211], v177 offset:34816
	ds_read_b128 v[212:215], v177 offset:35840
	ds_read_b128 v[216:219], v177 offset:36864
	ds_read_b128 v[220:223], v177 offset:37888
	ds_read_b128 v[224:227], v177 offset:38912
	ds_read_b128 v[228:231], v177 offset:39936
	global_load_lds_dwordx4 v[238:239], off
	v_lshl_add_u64 v[238:239], s[54:55], 0, v[140:141]
	s_mov_b32 m0, s61
	s_nop 0
	global_load_lds_dwordx4 v[238:239], off
	s_waitcnt vmcnt(8)
	s_waitcnt lgkmcnt(0)
	s_barrier
	s_setprio 1
	s_waitcnt lgkmcnt(0)
	v_mfma_f32_16x16x32_bf16 v[128:131], v[132:135], v[200:203], v[128:131]
	v_mfma_f32_16x16x32_bf16 v[124:127], v[148:151], v[200:203], v[124:127]
	v_mfma_f32_16x16x32_bf16 v[112:115], v[132:135], v[208:211], v[112:115]
	v_mfma_f32_16x16x32_bf16 v[108:111], v[148:151], v[208:211], v[108:111]
	v_mfma_f32_16x16x32_bf16 v[96:99], v[132:135], v[216:219], v[96:99]
	v_mfma_f32_16x16x32_bf16 v[92:95], v[148:151], v[216:219], v[92:95]
	v_mfma_f32_16x16x32_bf16 v[80:83], v[132:135], v[224:227], v[80:83]
	v_mfma_f32_16x16x32_bf16 v[76:79], v[148:151], v[224:227], v[76:79]
	v_mfma_f32_16x16x32_bf16 v[128:131], v[136:139], v[204:207], v[128:131]
	v_mfma_f32_16x16x32_bf16 v[124:127], v[152:155], v[204:207], v[124:127]
	v_mfma_f32_16x16x32_bf16 v[112:115], v[136:139], v[212:215], v[112:115]
	v_mfma_f32_16x16x32_bf16 v[108:111], v[152:155], v[212:215], v[108:111]
	v_mfma_f32_16x16x32_bf16 v[96:99], v[136:139], v[220:223], v[96:99]
	v_mfma_f32_16x16x32_bf16 v[92:95], v[152:155], v[220:223], v[92:95]
	v_mfma_f32_16x16x32_bf16 v[80:83], v[136:139], v[228:231], v[80:83]
	v_mfma_f32_16x16x32_bf16 v[76:79], v[152:155], v[228:231], v[76:79]
	s_setprio 0
	s_setprio 1
	v_mfma_f32_16x16x32_bf16 v[120:123], v[178:181], v[200:203], v[120:123]
	v_mfma_f32_16x16x32_bf16 v[116:119], v[186:189], v[200:203], v[116:119]
	v_mfma_f32_16x16x32_bf16 v[104:107], v[178:181], v[208:211], v[104:107]
	v_mfma_f32_16x16x32_bf16 v[100:103], v[186:189], v[208:211], v[100:103]
	v_mfma_f32_16x16x32_bf16 v[88:91], v[178:181], v[216:219], v[88:91]
	v_mfma_f32_16x16x32_bf16 v[84:87], v[186:189], v[216:219], v[84:87]
	v_mfma_f32_16x16x32_bf16 v[72:75], v[178:181], v[224:227], v[72:75]
	v_mfma_f32_16x16x32_bf16 v[68:71], v[186:189], v[224:227], v[68:71]
	v_mfma_f32_16x16x32_bf16 v[120:123], v[182:185], v[204:207], v[120:123]
	v_mfma_f32_16x16x32_bf16 v[116:119], v[190:193], v[204:207], v[116:119]
	v_mfma_f32_16x16x32_bf16 v[104:107], v[182:185], v[212:215], v[104:107]
	v_mfma_f32_16x16x32_bf16 v[100:103], v[190:193], v[212:215], v[100:103]
	v_mfma_f32_16x16x32_bf16 v[88:91], v[182:185], v[220:223], v[88:91]
	v_mfma_f32_16x16x32_bf16 v[84:87], v[190:193], v[220:223], v[84:87]
	v_mfma_f32_16x16x32_bf16 v[72:75], v[182:185], v[228:231], v[72:75]
	v_mfma_f32_16x16x32_bf16 v[68:71], v[190:193], v[228:231], v[68:71]
	s_setprio 0
	s_barrier
	s_add_i32 s24, s24, s22
	v_lshl_add_u64 v[172:173], v[172:173], 0, s[26:27]
	s_mov_b32 m0, s24
	ds_read_b128 v[200:203], v177 offset:49152
	ds_read_b128 v[204:207], v177 offset:50176
	ds_read_b128 v[208:211], v177 offset:51200
	ds_read_b128 v[212:215], v177 offset:52224
	ds_read_b128 v[216:219], v177 offset:53248
	ds_read_b128 v[220:223], v177 offset:54272
	ds_read_b128 v[224:227], v177 offset:55296
	ds_read_b128 v[228:231], v177 offset:56320
	global_load_lds_dwordx4 v[172:173], off
	s_add_i32 m0, s24, 0x2000
	s_add_u32 s14, s14, 0x40080
	v_lshl_add_u64 v[172:173], v[232:233], 0, s[26:27]
	s_addc_u32 s15, s15, 0
	s_add_i32 s24, s25, s22
	global_load_lds_dwordx4 v[172:173], off
	v_lshl_add_u64 v[172:173], s[14:15], 0, v[2:3]
	s_mov_b32 m0, s24
	s_nop 0
	global_load_lds_dwordx4 v[172:173], off
	v_lshl_add_u64 v[172:173], s[14:15], 0, v[0:1]
	s_add_i32 m0, s24, 0x2000
	s_nop 0
	global_load_lds_dwordx4 v[172:173], off
	v_lshl_add_u64 v[172:173], v[234:235], 0, s[26:27]
	s_mov_b32 m0, s64
	s_nop 0
	global_load_lds_dwordx4 v[172:173], off
	v_lshl_add_u64 v[172:173], v[236:237], 0, s[26:27]
	s_mov_b32 m0, s65
	s_nop 0
	global_load_lds_dwordx4 v[172:173], off
	s_waitcnt vmcnt(8)
	s_waitcnt lgkmcnt(0)
	s_barrier
	s_setprio 1
	s_waitcnt lgkmcnt(0)
	v_mfma_f32_16x16x32_bf16 v[64:67], v[132:135], v[200:203], v[64:67]
	v_mfma_f32_16x16x32_bf16 v[60:63], v[148:151], v[200:203], v[60:63]
	v_mfma_f32_16x16x32_bf16 v[48:51], v[132:135], v[208:211], v[48:51]
	v_mfma_f32_16x16x32_bf16 v[44:47], v[148:151], v[208:211], v[44:47]
	v_mfma_f32_16x16x32_bf16 v[32:35], v[132:135], v[216:219], v[32:35]
	v_mfma_f32_16x16x32_bf16 v[28:31], v[148:151], v[216:219], v[28:31]
	v_mfma_f32_16x16x32_bf16 v[16:19], v[132:135], v[224:227], v[16:19]
	v_mfma_f32_16x16x32_bf16 v[12:15], v[148:151], v[224:227], v[12:15]
	v_mfma_f32_16x16x32_bf16 v[64:67], v[136:139], v[204:207], v[64:67]
	v_mfma_f32_16x16x32_bf16 v[60:63], v[152:155], v[204:207], v[60:63]
	v_mfma_f32_16x16x32_bf16 v[48:51], v[136:139], v[212:215], v[48:51]
	v_mfma_f32_16x16x32_bf16 v[44:47], v[152:155], v[212:215], v[44:47]
	v_mfma_f32_16x16x32_bf16 v[32:35], v[136:139], v[220:223], v[32:35]
	v_mfma_f32_16x16x32_bf16 v[28:31], v[152:155], v[220:223], v[28:31]
	v_mfma_f32_16x16x32_bf16 v[16:19], v[136:139], v[228:231], v[16:19]
	v_mfma_f32_16x16x32_bf16 v[12:15], v[152:155], v[228:231], v[12:15]
	s_setprio 0
	s_setprio 1
	v_mfma_f32_16x16x32_bf16 v[56:59], v[178:181], v[200:203], v[56:59]
	v_mfma_f32_16x16x32_bf16 v[52:55], v[186:189], v[200:203], v[52:55]
	v_mfma_f32_16x16x32_bf16 v[40:43], v[178:181], v[208:211], v[40:43]
	v_mfma_f32_16x16x32_bf16 v[36:39], v[186:189], v[208:211], v[36:39]
	v_mfma_f32_16x16x32_bf16 v[24:27], v[178:181], v[216:219], v[24:27]
	v_mfma_f32_16x16x32_bf16 v[20:23], v[186:189], v[216:219], v[20:23]
	v_mfma_f32_16x16x32_bf16 v[8:11], v[178:181], v[224:227], v[8:11]
	v_mfma_f32_16x16x32_bf16 v[4:7], v[186:189], v[224:227], v[4:7]
	v_mfma_f32_16x16x32_bf16 v[56:59], v[182:185], v[204:207], v[56:59]
	v_mfma_f32_16x16x32_bf16 v[52:55], v[190:193], v[204:207], v[52:55]
	v_mfma_f32_16x16x32_bf16 v[40:43], v[182:185], v[212:215], v[40:43]
	v_mfma_f32_16x16x32_bf16 v[36:39], v[190:193], v[212:215], v[36:39]
	v_mfma_f32_16x16x32_bf16 v[24:27], v[182:185], v[220:223], v[24:27]
	v_mfma_f32_16x16x32_bf16 v[20:23], v[190:193], v[220:223], v[20:23]
	v_mfma_f32_16x16x32_bf16 v[8:11], v[182:185], v[228:231], v[8:11]
	v_mfma_f32_16x16x32_bf16 v[4:7], v[190:193], v[228:231], v[4:7]
	s_setprio 0
	s_barrier
	s_add_i32 s91, s91, 2
	s_add_u32 s87, s87, 0x100
	s_addc_u32 s89, s89, 0
	s_add_u32 s42, s42, 0x100
	s_addc_u32 s43, s43, 0
	s_cmp_gt_u32 s91, 13
	s_cbranch_scc0 .LBB0_812
	s_and_b64 vcc, exec, s[12:13]
	s_cbranch_vccz .LBB0_815
	s_barrier
